# POOLMIX pooling: rotate channel-group by row chunk so each SIMD gets one task of each window width (was all W16 tasks on SIMD3)
# speedup vs baseline: 1.0050x; 1.0050x over previous
.LBB0_321:
	s_lshr_b32 s52, s74, 4
	s_add_i32 s52, s52, s46
	s_and_b32 s47, s52, 3
	v_and_b32_e32 v0, 63, v208
	v_lshlrev_b32_e32 v0, 3, v0
	v_lshl_or_b32 v0, s47, 9, v0
	v_lshl_add_u64 v[214:215], s[36:37], 0, v[0:1]
	v_mov_b32_e32 v242, v0
	s_and_b32 s16, s74, -16
	s_add_i32 s40, s16, s63
	s_cmp_lt_i32 s47, 2
	s_mov_b64 s[26:27], -1
	s_cbranch_scc1 .LBB0_435
	s_cmp_gt_i32 s47, 2
	s_cbranch_scc0 .LBB0_386
	s_add_i32 s2, s40, 0xffff8000
	s_and_b32 s6, s40, 0x7f0
	s_add_i32 s17, s40, -15
	s_cmp_lt_i32 s40, 0x8000
	s_cselect_b64 s[26:27], -1, 0
	s_and_b64 s[18:19], s[26:27], exec
	s_cselect_b32 s2, s6, s2
	s_cselect_b32 s6, 0x8001, -1
	s_cmp_eq_u32 s2, 0
	s_cselect_b64 s[50:51], -1, 0
	s_and_b64 s[18:19], s[50:51], exec
	s_cselect_b32 s2, s6, s17
	s_cmp_gt_i32 s2, -1
	s_cselect_b32 s58, s2, s40
	s_ashr_i32 s59, s58, 31
	s_lshl_b64 s[18:19], s[58:59], 11
	s_waitcnt lgkmcnt(0)
	v_lshl_add_u64 v[2:3], v[214:215], 0, s[18:19]
	global_load_dwordx2 v[26:27], v[2:3], off
	s_cmp_lt_i32 s2, 0
	v_mov_b32_e32 v12, 0
	v_mov_b32_e32 v36, 0
	s_cbranch_scc1 .LBB0_325
	s_lshl_b64 s[18:19], s[58:59], 2
	s_add_u32 s18, s86, s18
	s_addc_u32 s19, s87, s19
	global_load_dword v36, v1, s[18:19]
